# attention: per-MFMA-group s_setprio toggles replaced by one static priority raise for waves 4-7 (s_nop kept in place of the toggles for hazard distances)
# baseline (speedup 1.0000x reference)
; __device__ __forceinline__ void attn_phase(LAS unsigned char* lds, const bf16* Q, const bf16* KV, const bf16* KPE, const float* rope, bf16* mix, int bid, int G, int tid) {
;     ...
;     for (int round = 0; round * G < AT_UNITS; ++round) {
;         int idx;
;         if (G == 256) { const int i2 = bid >> 1, od = bid & 1;
;             idx = (round == 0) ? bid : (round == 1 ? 256 + (od ? 127 - i2 : 255 - i2) : 512 + (od ? 255 - i2 : 127 - i2)); }
;         else idx = (round & 1) ? (round * G + (G - 1 - bid)) : (round * G + bid);
;         if (idx >= AT_UNITS) continue;
;         int tid_r = tid; asm volatile("" : "+v"(tid_r));
;         const int lane = tid_r & 63, l32 = lane & 31, hh = lane >> 5;
;         const int sr16 = tid_r >> 4, sc16 = tid_r & 15, sr8 = tid_r >> 3, sc8 = tid_r & 7;
;         const int qb = 15 - idx / 48, bh = idx % 48, b = bh / 12, h = bh - b * 12;
;         const int q0 = qb * 256, mrow0 = b * SEQ, ntiles = (qb + 1) * 4;
; __global__ void __launch_bounds__(NTHREADS, 2) trunk_fwd(Args a) {
;     ...
;         } else if (kind == 23) {
;             attn_phase(lds, QB, KVB, KPE, ROPE, MIX, bid, G, tid);
.LBB0_231:
	s_lshr_b32 s96, s59, 1
	s_and_b64 vcc, exec, s[0:1]
	s_cbranch_vccz .LBB0_471
	s_add_u32 s44, s88, 0x35610000
	s_addc_u32 s45, s89, 0
	s_bitcmp1_b32 s59, 0
	s_cselect_b32 s97, 0x4200000, 0
	s_add_u32 s22, s88, 0x9e00000
	s_addc_u32 s23, s89, 0
	s_cmp_lt_u32 s77, 28
	s_cselect_b64 s[0:1], -1, 0
	s_lshr_b32 s2, 0x9000240, s77
	s_bitcmp1_b32 s2, 0
	s_cselect_b64 s[4:5], -1, 0
	s_and_b64 s[4:5], s[0:1], s[4:5]
	s_andn2_b64 vcc, exec, s[4:5]
	s_mov_b64 s[4:5], -1
	s_cbranch_vccz .LBB0_424
	s_add_u32 s75, s88, 0x7200000
	s_addc_u32 s79, s89, 0
	s_lshr_b32 s2, 0x4000100, s77
	s_bitcmp1_b32 s2, 0
	s_cselect_b64 s[4:5], -1, 0
	s_and_b64 s[0:1], s[0:1], s[4:5]
	s_andn2_b64 vcc, exec, s[0:1]
	s_mov_b64 s[0:1], -1
	s_cbranch_vccz .LBB0_407
	s_add_u32 s80, s88, 0x33600000
	s_addc_u32 s81, s89, 0
	s_cmp_lt_i32 s77, 5
	s_cbranch_scc1 .LBB0_321
	s_cmp_lt_i32 s77, 21
	s_cbranch_scc1 .LBB0_275
	s_cmp_lt_i32 s77, 23
	s_cbranch_scc1 .LBB0_264
	s_cmp_eq_u32 s77, 23
	s_cbranch_scc0 .LBB0_263
	v_readfirstlane_b32 s0, v186
	s_cmp_ge_u32 s0, 0x100
	s_cbranch_scc0 .Latt_lo
	s_setprio 1
.Latt_lo:
	s_ashr_i32 s0, s0, 1
	s_and_b32 s2, s0, 0xffffffe0
	s_addk_i32 s2, 0xf00
	s_mov_b32 s5, 0
	s_mov_b32 s6, 0
	s_branch .LBB0_241

; #define LAS __attribute__((address_space(3)))
; #define AT_LDK(buf, grp) do { _Pragma("unroll") for (int q_ = 0; q_ < 2; ++q_) { kf[buf][2 * q_] = *(const LAS bf16x8*)(ka + ((grp) * 2 + q_) * 32); kf[buf][2 * q_ + 1] = *(const LAS bf16x8*)(ka + 32 * AT_KROW + ((grp) * 2 + q_) * 32); } } while (0)
; #define AT_LDV(buf, hs) do { const LAS unsigned char* vp_ = va + ((((hs) >> 1) >> 1) * 32 + 16 * (((hs) >> 1) & 1)) * AT_VROW + ((hs) & 1) * 128; _Pragma("unroll") for (int d_ = 0; d_ < 2; ++d_) { vf[buf][2 * d_] = vtr(vp_ + d_ * 64); vf[buf][2 * d_ + 1] = vtr(vp_ + 8 * AT_VROW + d_ * 64); } } while (0)
; __device__ __forceinline__ void attn_phase(LAS unsigned char* lds, const bf16* Q, const bf16* KV, const bf16* KPE, const float* rope, bf16* mix, int bid, int G, int tid) {
;     ...
;             if (key0 <= qlo + 31) {
;                 f32x16 S0, S1;
; #pragma unroll
;                 for (int e = 0; e < 16; ++e) { S0[e] = 0.f; S1[e] = 0.f; }
;                 const LAS unsigned char* ka = kb_ + l32 * AT_KROW + hh * 16;
;                 bf16x8 kf[2][4];
;     ...
;                 AT_LDK(0, 0); __builtin_amdgcn_sched_barrier(0);
; #pragma unroll
;                 for (int grp = 0; grp < 6; ++grp) {
;                     if (grp < 5) { AT_LDK((grp + 1) & 1, grp + 1); }
;                     __builtin_amdgcn_sched_barrier(0);
;                     __builtin_amdgcn_s_setprio(1);
; #pragma unroll
;                     for (int q_ = 0; q_ < 2; ++q_) {
;                         S0 = __builtin_amdgcn_mfma_f32_32x32x16_bf16(kf[grp & 1][2 * q_], qf[grp * 2 + q_], S0, 0, 0, 0);
;                         S1 = __builtin_amdgcn_mfma_f32_32x32x16_bf16(kf[grp & 1][2 * q_ + 1], qf[grp * 2 + q_], S1, 0, 0, 0); }
;                     __builtin_amdgcn_s_setprio(0);
;                     __builtin_amdgcn_sched_barrier(0); }
;     ...
;                 const LAS unsigned char* va = vb_ + (4 * hh + ((lane & 15) >> 2)) * AT_VROW + (16 * ((lane >> 4) & 1) + 4 * (lane & 3)) * 2;
;                 s16x4 vf[2][4];
;     ...
;                 AT_LDV(0, 0); __builtin_amdgcn_sched_barrier(0);
;                 if (key0 + 63 > qlo) { const int qq = qlo + l32;
; #pragma unroll
;                     for (int e = 0; e < 16; ++e) { const int key = key0 + 8 * (e >> 2) + 4 * hh + (e & 3);
;                         if (key > qq) S0[e] = -1e30f; if (key + 32 > qq) S1[e] = -1e30f; } }
.LBB0_253:
	s_sub_i32 s5, s0, 63
	s_cmp_gt_i32 s5, s11
	s_cbranch_scc1 .LBB0_259
	s_bitcmp1_b32 s4, 0
	s_cselect_b32 s4, 0xb400, 0
	s_add_i32 s4, s4, 0
	v_add3_u32 v236, s4, v203, v96
	ds_read_b128 v[64:67], v236
	ds_read_b128 v[166:169], v236 offset:32
	ds_read_b128 v[68:71], v236 offset:12800
	ds_read_b128 v[170:173], v236 offset:12832
	ds_read_b128 v[208:211], v236 offset:64
	ds_read_b128 v[212:215], v236 offset:96
	ds_read_b128 v[228:231], v236 offset:12864
	ds_read_b128 v[232:235], v236 offset:12896
	s_nop 0
	s_waitcnt lgkmcnt(0)
	v_mfma_f32_32x32x16_bf16 v[80:95], v[64:67], v[98:101], 0
	v_mfma_f32_32x32x16_bf16 v[64:79], v[68:71], v[98:101], 0
	v_mfma_f32_32x32x16_bf16 v[80:95], v[166:169], v[102:105], v[80:95]
	v_mfma_f32_32x32x16_bf16 v[64:79], v[170:173], v[102:105], v[64:79]
	s_nop 0
	ds_read_b128 v[166:169], v236 offset:128
	ds_read_b128 v[170:173], v236 offset:160
	ds_read_b128 v[242:245], v236 offset:12928
	ds_read_b128 v[246:249], v236 offset:12960
	s_nop 0
	v_mfma_f32_32x32x16_bf16 v[80:95], v[208:211], v[106:109], v[80:95]
	v_mfma_f32_32x32x16_bf16 v[64:79], v[228:231], v[106:109], v[64:79]
	v_mfma_f32_32x32x16_bf16 v[80:95], v[212:215], v[110:113], v[80:95]
	v_mfma_f32_32x32x16_bf16 v[64:79], v[232:235], v[110:113], v[64:79]
	s_nop 0
	ds_read_b128 v[208:211], v236 offset:192
	ds_read_b128 v[212:215], v236 offset:224
	ds_read_b128 v[228:231], v236 offset:12992
	ds_read_b128 v[232:235], v236 offset:13024
	s_nop 0
	s_waitcnt lgkmcnt(0)
	v_mfma_f32_32x32x16_bf16 v[80:95], v[166:169], v[114:117], v[80:95]
	v_mfma_f32_32x32x16_bf16 v[64:79], v[242:245], v[114:117], v[64:79]
	v_mfma_f32_32x32x16_bf16 v[80:95], v[170:173], v[118:121], v[80:95]
	v_mfma_f32_32x32x16_bf16 v[64:79], v[246:249], v[118:121], v[64:79]
	s_nop 0
	ds_read_b128 v[166:169], v236 offset:256
	ds_read_b128 v[170:173], v236 offset:288
	ds_read_b128 v[242:245], v236 offset:13056
	ds_read_b128 v[246:249], v236 offset:13088
	s_nop 0
	v_mfma_f32_32x32x16_bf16 v[80:95], v[208:211], v[122:125], v[80:95]
	v_mfma_f32_32x32x16_bf16 v[64:79], v[228:231], v[122:125], v[64:79]
	v_mfma_f32_32x32x16_bf16 v[80:95], v[212:215], v[126:129], v[80:95]
	v_mfma_f32_32x32x16_bf16 v[64:79], v[232:235], v[126:129], v[64:79]
	s_nop 0
	ds_read_b128 v[208:211], v236 offset:320
	ds_read_b128 v[212:215], v236 offset:352
	ds_read_b128 v[228:231], v236 offset:13120
	ds_read_b128 v[232:235], v236 offset:13152
	s_nop 0
	s_waitcnt lgkmcnt(0)
	v_mfma_f32_32x32x16_bf16 v[80:95], v[166:169], v[130:133], v[80:95]
	v_mfma_f32_32x32x16_bf16 v[64:79], v[242:245], v[130:133], v[64:79]
	v_mfma_f32_32x32x16_bf16 v[80:95], v[170:173], v[158:161], v[80:95]
	v_mfma_f32_32x32x16_bf16 v[64:79], v[246:249], v[158:161], v[64:79]
	s_nop 0
	s_nop 0
	s_nop 0
	v_mfma_f32_32x32x16_bf16 v[80:95], v[208:211], v[134:137], v[80:95]
	v_add_u32_e32 v166, s4, v204
	v_add_u32_e32 v208, v166, v205
	ds_read_b64_tr_b16 v[170:171], v208 offset:25600
	ds_read_b64_tr_b16 v[172:173], v208 offset:28160
	ds_read_b64_tr_b16 v[168:169], v208 offset:28224
	ds_read_b64_tr_b16 v[166:167], v208 offset:25664
	v_mfma_f32_32x32x16_bf16 v[64:79], v[228:231], v[134:137], v[64:79]
	v_mfma_f32_32x32x16_bf16 v[80:95], v[212:215], v[162:165], v[80:95]
	v_mfma_f32_32x32x16_bf16 v[64:79], v[232:235], v[162:165], v[64:79]
	s_cmp_le_i32 s0, s8
	s_cbranch_scc1 .LBB0_256
	v_add_u32_e32 v209, s0, v189
	v_subrev_u32_e32 v211, 31, v209
	v_subrev_u32_e32 v210, 63, v209
	v_cmp_le_i32_e32 vcc, v211, v206
	s_nop 5
	v_cndmask_b32_e32 v64, v224, v64, vcc
	v_cmp_lt_i32_e32 vcc, v210, v206
	s_nop 1
	v_cndmask_b32_e32 v81, v224, v81, vcc
	v_cmp_le_i32_e32 vcc, v210, v206
	v_subrev_u32_e32 v210, 30, v209
	s_nop 0
	v_cndmask_b32_e32 v80, v224, v80, vcc
	v_cmp_le_i32_e32 vcc, v210, v206
	v_subrev_u32_e32 v210, 61, v209
	s_nop 0
	v_cndmask_b32_e32 v65, v224, v65, vcc
	v_cmp_le_i32_e32 vcc, v210, v206
	v_subrev_u32_e32 v210, 29, v209
	s_nop 0
	v_cndmask_b32_e32 v82, v224, v82, vcc
	v_cmp_le_i32_e32 vcc, v210, v206
	v_subrev_u32_e32 v210, 60, v209
	s_nop 0
	v_cndmask_b32_e32 v66, v224, v66, vcc
	v_cmp_le_i32_e32 vcc, v210, v206
	v_subrev_u32_e32 v210, 28, v209
	s_nop 0
	v_cndmask_b32_e32 v83, v224, v83, vcc
	v_cmp_le_i32_e32 vcc, v210, v206
	v_subrev_u32_e32 v210, 55, v209
	s_nop 0
	v_cndmask_b32_e32 v67, v224, v67, vcc
	v_cmp_le_i32_e32 vcc, v210, v206
	v_subrev_u32_e32 v210, 23, v209
	s_nop 0
	v_cndmask_b32_e32 v84, v224, v84, vcc
	v_cmp_le_i32_e32 vcc, v210, v206
	v_subrev_u32_e32 v210, 54, v209
	s_nop 0
	v_cndmask_b32_e32 v68, v224, v68, vcc
	v_cmp_le_i32_e32 vcc, v210, v206
	v_subrev_u32_e32 v210, 22, v209
	s_nop 0
	v_cndmask_b32_e32 v85, v224, v85, vcc
	v_cmp_le_i32_e32 vcc, v210, v206
	v_subrev_u32_e32 v210, 53, v209
	s_nop 0
	v_cndmask_b32_e32 v69, v224, v69, vcc
	v_cmp_le_i32_e32 vcc, v210, v206
	v_subrev_u32_e32 v210, 21, v209
	s_nop 0
	v_cndmask_b32_e32 v86, v224, v86, vcc
	v_cmp_le_i32_e32 vcc, v210, v206
	v_subrev_u32_e32 v210, 52, v209
	s_nop 0
	v_cndmask_b32_e32 v70, v224, v70, vcc
	v_cmp_le_i32_e32 vcc, v210, v206
	v_subrev_u32_e32 v210, 20, v209
	s_nop 0
	v_cndmask_b32_e32 v87, v224, v87, vcc
	v_cmp_le_i32_e32 vcc, v210, v206
	v_subrev_u32_e32 v210, 47, v209
	s_nop 0
	v_cndmask_b32_e32 v71, v224, v71, vcc
	v_cmp_le_i32_e32 vcc, v210, v206
	v_add_u32_e32 v210, -15, v209
	s_nop 0
	v_cndmask_b32_e32 v88, v224, v88, vcc
	v_cmp_le_i32_e32 vcc, v210, v206
	v_subrev_u32_e32 v210, 46, v209
	s_nop 0
	v_cndmask_b32_e32 v72, v224, v72, vcc
	v_cmp_le_i32_e32 vcc, v210, v206
	v_add_u32_e32 v210, -14, v209
	s_nop 0
	v_cndmask_b32_e32 v89, v224, v89, vcc
	v_cmp_le_i32_e32 vcc, v210, v206
	v_subrev_u32_e32 v210, 45, v209
	s_nop 0
	v_cndmask_b32_e32 v73, v224, v73, vcc
	v_cmp_le_i32_e32 vcc, v210, v206
	v_add_u32_e32 v210, -13, v209
	s_nop 0
	v_cndmask_b32_e32 v90, v224, v90, vcc
	v_cmp_le_i32_e32 vcc, v210, v206
	v_subrev_u32_e32 v210, 44, v209
	s_nop 0
	v_cndmask_b32_e32 v74, v224, v74, vcc
	v_cmp_le_i32_e32 vcc, v210, v206
	v_add_u32_e32 v210, -12, v209
	s_nop 0
	v_cndmask_b32_e32 v91, v224, v91, vcc
	v_cmp_le_i32_e32 vcc, v210, v206
	v_subrev_u32_e32 v210, 39, v209
	s_nop 0
	v_cndmask_b32_e32 v75, v224, v75, vcc
	v_cmp_le_i32_e32 vcc, v210, v206
	v_add_u32_e32 v210, -7, v209
	s_nop 0
	v_cndmask_b32_e32 v92, v224, v92, vcc
	v_cmp_le_i32_e32 vcc, v210, v206
	v_subrev_u32_e32 v210, 38, v209
	s_nop 0
	v_cndmask_b32_e32 v76, v224, v76, vcc
	v_cmp_le_i32_e32 vcc, v210, v206
	v_add_u32_e32 v210, -6, v209
	s_nop 0
	v_cndmask_b32_e32 v93, v224, v93, vcc
	v_cmp_le_i32_e32 vcc, v210, v206
	v_subrev_u32_e32 v210, 37, v209
	s_nop 0
	v_cndmask_b32_e32 v77, v224, v77, vcc
	v_cmp_le_i32_e32 vcc, v210, v206
	v_add_u32_e32 v210, -5, v209
	s_nop 0
	v_cndmask_b32_e32 v94, v224, v94, vcc
	v_cmp_le_i32_e32 vcc, v210, v206
	v_subrev_u32_e32 v210, 36, v209
	v_add_u32_e32 v209, -4, v209
	v_cndmask_b32_e32 v78, v224, v78, vcc
	v_cmp_le_i32_e32 vcc, v210, v206
	s_nop 1
	v_cndmask_b32_e32 v95, v224, v95, vcc
	v_cmp_le_i32_e32 vcc, v209, v206
	s_nop 1
	v_cndmask_b32_e32 v79, v224, v79, vcc

; __device__ __forceinline__ u32x4 pack8(const float (&f)[8]) { u32x4 w; w.x = pk_bf16(f[0], f[1]); w.y = pk_bf16(f[2], f[3]); w.z = pk_bf16(f[4], f[5]); w.w = pk_bf16(f[6], f[7]); return w; }
; __device__ __forceinline__ void attn_phase(LAS unsigned char* lds, const bf16* Q, const bf16* KV, const bf16* KPE, const float* rope, bf16* mix, int bid, int G, int tid) {
;     ...
;                 float mx = fmaxf(S0[0], S1[0]);
; #pragma unroll
;                 for (int e = 1; e < 16; ++e) mx = fmaxf(mx, fmaxf(S0[e], S1[e]));
;                 mx = fmaxf(mx, __shfl_xor(mx, 32));
;                 const float mnew = (mx > mrun + 6.0f) ? mx : mrun;
;                 const float alpha = __builtin_amdgcn_exp2f(mrun - mnew); mrun = mnew;
;                 float rs = 0.f;
; #pragma unroll
;                 for (int e = 0; e < 16; ++e) { S0[e] = __builtin_amdgcn_exp2f(S0[e] - mnew); S1[e] = __builtin_amdgcn_exp2f(S1[e] - mnew); rs += S0[e] + S1[e]; }
;                 lrun = lrun * alpha + rs;
;                 if (__builtin_amdgcn_ballot_w64(alpha != 1.0f) != 0ull) {
; #pragma unroll
;                     for (int i = 0; i < 4; ++i)
; #pragma unroll
;                         for (int e = 0; e < 16; ++e) O[i][e] *= alpha; }
; #pragma unroll
;                 for (int hs = 0; hs < 8; ++hs) { const int st = hs >> 1;
;                     if (hs < 7) { AT_LDV((hs + 1) & 1, hs + 1); }
;                     __builtin_amdgcn_sched_barrier(0);
;                     float pf[8];
; #pragma unroll
;                     for (int e = 0; e < 8; ++e) pf[e] = (st >> 1) ? S1[8 * (st & 1) + e] : S0[8 * (st & 1) + e];
;                     const bf16x8 pb = __builtin_bit_cast(bf16x8, pack8(pf));
; #pragma unroll
;                     for (int d_ = 0; d_ < 2; ++d_) { const int dvt = (hs & 1) * 2 + d_; const s16x4 lo = vf[hs & 1][2 * d_], hi = vf[hs & 1][2 * d_ + 1];
;                         const bf16x8 A = (bf16x8){lo[0], lo[1], lo[2], lo[3], hi[0], hi[1], hi[2], hi[3]};
;                         __builtin_amdgcn_s_setprio(1); O[dvt] = __builtin_amdgcn_mfma_f32_32x32x16_bf16(A, pb, O[dvt], 0, 0, 0); __builtin_amdgcn_s_setprio(0); }
;                     __builtin_amdgcn_sched_barrier(0); }
.LBB0_258:
	v_sub_f32_e32 v80, v80, v209
	v_sub_f32_e32 v64, v64, v209
	v_exp_f32_e32 v80, v80
	v_exp_f32_e32 v210, v64
	v_sub_f32_e32 v81, v81, v209
	v_sub_f32_e32 v65, v65, v209
	v_exp_f32_e32 v81, v81
	v_exp_f32_e32 v211, v65
	v_add_f32_e32 v64, v80, v210
	v_add_f32_e32 v64, 0, v64
	v_add_f32_e32 v65, v81, v211
	v_add_f32_e32 v64, v65, v64
	v_sub_f32_e32 v65, v82, v209
	v_exp_f32_e32 v82, v65
	v_sub_f32_e32 v65, v66, v209
	v_exp_f32_e32 v212, v65
	s_nop 0
	v_add_f32_e32 v65, v82, v212
	v_add_f32_e32 v64, v65, v64
	v_sub_f32_e32 v65, v83, v209
	v_exp_f32_e32 v83, v65
	v_sub_f32_e32 v65, v67, v209
	v_exp_f32_e32 v213, v65
	s_nop 0
	v_add_f32_e32 v65, v83, v213
	v_add_f32_e32 v64, v65, v64
	v_sub_f32_e32 v65, v84, v209
	v_exp_f32_e32 v84, v65
	v_sub_f32_e32 v65, v68, v209
	v_exp_f32_e32 v214, v65
	s_nop 0
	v_add_f32_e32 v65, v84, v214
	v_add_f32_e32 v64, v65, v64
	v_sub_f32_e32 v65, v85, v209
	v_exp_f32_e32 v85, v65
	v_sub_f32_e32 v65, v69, v209
	v_exp_f32_e32 v215, v65
	s_nop 0
	v_add_f32_e32 v65, v85, v215
	v_add_f32_e32 v64, v65, v64
	v_sub_f32_e32 v65, v86, v209
	v_exp_f32_e32 v86, v65
	v_sub_f32_e32 v65, v70, v209
	v_exp_f32_e32 v228, v65
	s_nop 0
	v_add_f32_e32 v65, v86, v228
	v_add_f32_e32 v64, v65, v64
	v_sub_f32_e32 v65, v87, v209
	v_exp_f32_e32 v87, v65
	v_sub_f32_e32 v65, v71, v209
	v_exp_f32_e32 v229, v65
	s_nop 0
	v_add_f32_e32 v65, v87, v229
	v_add_f32_e32 v64, v65, v64
	v_sub_f32_e32 v65, v88, v209
	v_exp_f32_e32 v88, v65
	v_sub_f32_e32 v65, v72, v209
	v_exp_f32_e32 v230, v65
	s_nop 0
	v_add_f32_e32 v65, v88, v230
	v_add_f32_e32 v64, v65, v64
	v_sub_f32_e32 v65, v89, v209
	v_exp_f32_e32 v89, v65
	v_sub_f32_e32 v65, v73, v209
	v_exp_f32_e32 v231, v65
	s_nop 0
	v_add_f32_e32 v65, v89, v231
	v_add_f32_e32 v64, v65, v64
	v_sub_f32_e32 v65, v90, v209
	v_exp_f32_e32 v90, v65
	v_sub_f32_e32 v65, v74, v209
	v_exp_f32_e32 v232, v65
	s_nop 0
	v_add_f32_e32 v65, v90, v232
	v_add_f32_e32 v64, v65, v64
	v_sub_f32_e32 v65, v91, v209
	v_exp_f32_e32 v91, v65
	v_sub_f32_e32 v65, v75, v209
	v_exp_f32_e32 v233, v65
	s_nop 0
	v_add_f32_e32 v65, v91, v233
	v_add_f32_e32 v64, v65, v64
	v_sub_f32_e32 v65, v92, v209
	v_exp_f32_e32 v92, v65
	v_sub_f32_e32 v65, v76, v209
	v_exp_f32_e32 v234, v65
	s_nop 0
	v_add_f32_e32 v65, v92, v234
	v_add_f32_e32 v64, v65, v64
	v_sub_f32_e32 v65, v93, v209
	v_exp_f32_e32 v93, v65
	v_sub_f32_e32 v65, v77, v209
	v_exp_f32_e32 v235, v65
	s_nop 0
	v_add_f32_e32 v65, v93, v235
	v_add_f32_e32 v64, v65, v64
	v_sub_f32_e32 v65, v94, v209
	v_exp_f32_e32 v94, v65
	v_sub_f32_e32 v65, v78, v209
	v_exp_f32_e32 v236, v65
	s_nop 0
	v_add_f32_e32 v65, v94, v236
	v_add_f32_e32 v64, v65, v64
	v_sub_f32_e32 v65, v95, v209
	v_exp_f32_e32 v95, v65
	v_sub_f32_e32 v65, v79, v209
	v_exp_f32_e32 v237, v65
	s_nop 0
	v_add_f32_e32 v65, v95, v237
	v_add_f32_e32 v242, v65, v64
	ds_read_b64_tr_b16 v[64:65], v208 offset:25728
	ds_read_b64_tr_b16 v[66:67], v208 offset:28288
	ds_read_b64_tr_b16 v[68:69], v208 offset:25792
	ds_read_b64_tr_b16 v[70:71], v208 offset:28352
	v_fmac_f32_e32 v242, v207, v184
	v_cvt_pk_bf16_f32 v72, v80, v81
	v_cvt_pk_bf16_f32 v73, v82, v83
	v_cvt_pk_bf16_f32 v74, v84, v85
	v_cvt_pk_bf16_f32 v75, v86, v87
	s_nop 0
	s_nop 0
	v_mfma_f32_32x32x16_bf16 v[48:63], v[170:173], v[72:75], v[48:63]
	s_nop 0
	s_nop 0
	v_mfma_f32_32x32x16_bf16 v[32:47], v[166:169], v[72:75], v[32:47]
	s_nop 0
	ds_read_b64_tr_b16 v[76:77], v208 offset:30720
	ds_read_b64_tr_b16 v[78:79], v208 offset:33280
	ds_read_b64_tr_b16 v[80:81], v208 offset:30784
	ds_read_b64_tr_b16 v[82:83], v208 offset:33344
	s_nop 0
	s_waitcnt lgkmcnt(0)
	v_mfma_f32_32x32x16_bf16 v[16:31], v[64:67], v[72:75], v[16:31]
	s_nop 0
	s_nop 0
	v_mfma_f32_32x32x16_bf16 v[0:15], v[68:71], v[72:75], v[0:15]
	s_nop 0
	ds_read_b64_tr_b16 v[64:65], v208 offset:30848
	ds_read_b64_tr_b16 v[66:67], v208 offset:33408
	ds_read_b64_tr_b16 v[68:69], v208 offset:30912
	ds_read_b64_tr_b16 v[70:71], v208 offset:33472
	v_cvt_pk_bf16_f32 v72, v88, v89
	v_cvt_pk_bf16_f32 v73, v90, v91
	v_cvt_pk_bf16_f32 v74, v92, v93
	v_cvt_pk_bf16_f32 v75, v94, v95
	s_nop 0
	s_nop 0
	v_mfma_f32_32x32x16_bf16 v[48:63], v[76:79], v[72:75], v[48:63]
	s_nop 0
	s_nop 0
	v_mfma_f32_32x32x16_bf16 v[32:47], v[80:83], v[72:75], v[32:47]
	s_nop 0
	ds_read_b64_tr_b16 v[76:77], v208 offset:35840
	ds_read_b64_tr_b16 v[78:79], v208 offset:38400
	ds_read_b64_tr_b16 v[82:83], v208 offset:38464
	ds_read_b64_tr_b16 v[80:81], v208 offset:35904
	s_nop 0
	s_waitcnt lgkmcnt(0)
	v_mfma_f32_32x32x16_bf16 v[16:31], v[64:67], v[72:75], v[16:31]
	s_nop 0
	s_nop 0
	v_mfma_f32_32x32x16_bf16 v[0:15], v[68:71], v[72:75], v[0:15]
	s_nop 0
	ds_read_b64_tr_b16 v[64:65], v208 offset:35968
	ds_read_b64_tr_b16 v[66:67], v208 offset:38528
	ds_read_b64_tr_b16 v[70:71], v208 offset:38592
	ds_read_b64_tr_b16 v[68:69], v208 offset:36032
	v_cvt_pk_bf16_f32 v72, v210, v211
	v_cvt_pk_bf16_f32 v73, v212, v213
	v_cvt_pk_bf16_f32 v74, v214, v215
	v_cvt_pk_bf16_f32 v75, v228, v229
	s_nop 0
	s_nop 0
	v_mfma_f32_32x32x16_bf16 v[48:63], v[76:79], v[72:75], v[48:63]
	s_nop 0
	s_nop 0
	v_mfma_f32_32x32x16_bf16 v[32:47], v[80:83], v[72:75], v[32:47]
	s_nop 0
	ds_read_b64_tr_b16 v[76:77], v208 offset:40960
	ds_read_b64_tr_b16 v[78:79], v208 offset:43520
	ds_read_b64_tr_b16 v[82:83], v208 offset:43584
	ds_read_b64_tr_b16 v[80:81], v208 offset:41024
	s_nop 0
	s_waitcnt lgkmcnt(0)
	v_mfma_f32_32x32x16_bf16 v[16:31], v[64:67], v[72:75], v[16:31]
	s_nop 0
	s_nop 0
	v_mfma_f32_32x32x16_bf16 v[0:15], v[68:71], v[72:75], v[0:15]
	s_nop 0
	ds_read_b64_tr_b16 v[64:65], v208 offset:41088
	ds_read_b64_tr_b16 v[66:67], v208 offset:43648
	ds_read_b64_tr_b16 v[70:71], v208 offset:43712
	ds_read_b64_tr_b16 v[68:69], v208 offset:41152
	v_cvt_pk_bf16_f32 v72, v230, v231
	v_cvt_pk_bf16_f32 v73, v232, v233
	v_cvt_pk_bf16_f32 v74, v234, v235
	v_cvt_pk_bf16_f32 v75, v236, v237
	s_nop 0
	s_nop 0
	v_mfma_f32_32x32x16_bf16 v[48:63], v[76:79], v[72:75], v[48:63]
	s_nop 0
	s_nop 0
	v_mfma_f32_32x32x16_bf16 v[32:47], v[80:83], v[72:75], v[32:47]
	s_nop 0
	s_nop 0
	s_waitcnt lgkmcnt(0)
	v_mfma_f32_32x32x16_bf16 v[16:31], v[64:67], v[72:75], v[16:31]
	s_nop 0
	s_nop 0
	v_mfma_f32_32x32x16_bf16 v[0:15], v[68:71], v[72:75], v[0:15]
	s_nop 0
	v_mov_b32_e32 v207, v242
	s_andn2_b64 vcc, exec, s[34:35]
	s_cbranch_vccz .LBB0_260
	s_branch .LBB0_261

; __global__ void __launch_bounds__(NTHREADS, 2) trunk_fwd(Args a) {
;     ...
;         } else if (kind == 23) {
;             attn_phase(lds, QB, KVB, KPE, ROPE, MIX, bid, G, tid);
;         }
.LBB0_263:
	s_setprio 0
	s_mov_b64 s[0:1], 0
